# MFMA half raises its priority before issuing the start-up fragment reads instead of after them
# speedup vs baseline: 1.0022x; 1.0022x over previous
.Lwd_b1:
	s_barrier
	s_setprio 1
	ds_read_b64_tr_b16 v[96:97], v205 offset:34816
	ds_read_b64_tr_b16 v[98:99], v205 offset:37376
	ds_read_b64_tr_b16 v[100:101], v205 offset:39936
	ds_read_b64_tr_b16 v[102:103], v205 offset:42496
	ds_read_b64_tr_b16 v[104:105], v205 offset:45056
	ds_read_b64_tr_b16 v[106:107], v205 offset:47616
	ds_read_b64_tr_b16 v[108:109], v205 offset:50176
	ds_read_b64_tr_b16 v[110:111], v205 offset:52736
	ds_read_b64_tr_b16 v[176:177], v205 offset:34880
	ds_read_b64_tr_b16 v[178:179], v205 offset:37440
	ds_read_b64_tr_b16 v[180:181], v205 offset:40000
	ds_read_b64_tr_b16 v[182:183], v205 offset:42560
	ds_read_b64_tr_b16 v[184:185], v205 offset:45120
	ds_read_b64_tr_b16 v[186:187], v205 offset:47680
	s_waitcnt lgkmcnt(12)
	v_mfma_f32_32x32x16_bf16 v[32:47], v[96:99], v[80:83], v[32:47]
	ds_read_b64_tr_b16 v[96:97], v205 offset:50240
	ds_read_b64_tr_b16 v[98:99], v205 offset:52800
	s_waitcnt lgkmcnt(12)
	v_mfma_f32_32x32x16_bf16 v[32:47], v[100:103], v[84:87], v[32:47]
	ds_read_b64_tr_b16 v[100:101], v205 offset:34944
	ds_read_b64_tr_b16 v[102:103], v205 offset:37504
	s_waitcnt lgkmcnt(12)
	v_mfma_f32_32x32x16_bf16 v[32:47], v[104:107], v[88:91], v[32:47]
	ds_read_b64_tr_b16 v[104:105], v205 offset:40064
	ds_read_b64_tr_b16 v[106:107], v205 offset:42624
	s_waitcnt lgkmcnt(12)
	v_mfma_f32_32x32x16_bf16 v[32:47], v[108:111], v[92:95], v[32:47]
	ds_read_b64_tr_b16 v[108:109], v205 offset:45184
	ds_read_b64_tr_b16 v[110:111], v205 offset:47744
	s_waitcnt lgkmcnt(12)
	v_mfma_f32_32x32x16_bf16 v[16:31], v[176:179], v[80:83], v[16:31]
	ds_read_b64_tr_b16 v[176:177], v205 offset:50304
	ds_read_b64_tr_b16 v[178:179], v205 offset:52864
	s_waitcnt lgkmcnt(12)
	v_mfma_f32_32x32x16_bf16 v[16:31], v[180:183], v[84:87], v[16:31]
	ds_read_b64_tr_b16 v[180:181], v205 offset:35008
	ds_read_b64_tr_b16 v[182:183], v205 offset:37568
	s_waitcnt lgkmcnt(12)
	v_mfma_f32_32x32x16_bf16 v[16:31], v[184:187], v[88:91], v[16:31]
	ds_read_b64_tr_b16 v[184:185], v205 offset:40128
	ds_read_b64_tr_b16 v[186:187], v205 offset:42688
	s_waitcnt lgkmcnt(12)
	v_mfma_f32_32x32x16_bf16 v[16:31], v[96:99], v[92:95], v[16:31]
	ds_read_b64_tr_b16 v[96:97], v205 offset:45248
	ds_read_b64_tr_b16 v[98:99], v205 offset:47808
	s_waitcnt lgkmcnt(12)
	v_mfma_f32_32x32x16_bf16 v[0:15], v[100:103], v[80:83], v[0:15]
	ds_read_b64_tr_b16 v[100:101], v205 offset:50368
	ds_read_b64_tr_b16 v[102:103], v205 offset:52928
	s_waitcnt lgkmcnt(12)
	v_mfma_f32_32x32x16_bf16 v[0:15], v[104:107], v[84:87], v[0:15]
	ds_read_b128 v[210:213], v206 offset:8704
	ds_read_b128 v[104:107], v206 offset:8736
	s_waitcnt lgkmcnt(12)
	v_mfma_f32_32x32x16_bf16 v[0:15], v[108:111], v[88:91], v[0:15]
	ds_read_b128 v[108:111], v206 offset:8768
	ds_read_b128 v[188:191], v206
	s_waitcnt lgkmcnt(12)
	v_mfma_f32_32x32x16_bf16 v[0:15], v[176:179], v[92:95], v[0:15]
	ds_read_b128 v[176:179], v206 offset:8800
	ds_read_b128 v[224:227], v206 offset:32
	s_waitcnt lgkmcnt(12)
	v_mfma_f32_32x32x16_bf16 v[48:63], v[180:183], v[80:83], v[48:63]
	ds_read_b128 v[228:231], v206 offset:64
	ds_read_b128 v[248:251], v206 offset:96
	s_waitcnt lgkmcnt(12)
	v_mfma_f32_32x32x16_bf16 v[48:63], v[184:187], v[84:87], v[48:63]
	s_waitcnt lgkmcnt(10)
	v_mfma_f32_32x32x16_bf16 v[48:63], v[96:99], v[88:91], v[48:63]
	s_waitcnt lgkmcnt(8)
	v_mfma_f32_32x32x16_bf16 v[48:63], v[100:103], v[92:95], v[48:63]
	s_waitcnt lgkmcnt(7)
	v_mfma_f32_32x32x16_bf16 v[80:95], v[210:213], v[112:115], v[64:79]
	s_waitcnt lgkmcnt(6)
	v_mfma_f32_32x32x16_bf16 v[80:95], v[104:107], v[116:119], v[80:95]
	s_waitcnt lgkmcnt(5)
	v_mfma_f32_32x32x16_bf16 v[80:95], v[108:111], v[120:123], v[80:95]
	s_waitcnt lgkmcnt(3)
	v_mfma_f32_32x32x16_bf16 v[80:95], v[176:179], v[124:127], v[80:95]
	s_waitcnt lgkmcnt(4)
	v_mfma_f32_32x32x16_bf16 v[96:111], v[188:191], v[112:115], v[64:79]
	s_waitcnt lgkmcnt(2)
	v_mfma_f32_32x32x16_bf16 v[96:111], v[224:227], v[116:119], v[96:111]
	s_waitcnt lgkmcnt(1)
	v_mfma_f32_32x32x16_bf16 v[96:111], v[228:231], v[120:123], v[96:111]
	s_waitcnt lgkmcnt(0)
	v_mfma_f32_32x32x16_bf16 v[96:111], v[248:251], v[124:127], v[96:111]
	s_setprio 0
	s_cmp_gt_i32 s33, 3
	s_cbranch_scc0 .Lbn_b1

.LA1_top:
	s_setprio 1
	v_add_u32_e32 v205, 0x0, v165
	v_add_u32_e32 v206, 0x4400, v192
	ds_read_b64_tr_b16 v[96:97], v205 offset:34816
	ds_read_b64_tr_b16 v[98:99], v205 offset:37376
	ds_read_b64_tr_b16 v[100:101], v205 offset:39936
	ds_read_b64_tr_b16 v[102:103], v205 offset:42496
	ds_read_b64_tr_b16 v[104:105], v205 offset:45056
	ds_read_b64_tr_b16 v[106:107], v205 offset:47616
	ds_read_b64_tr_b16 v[108:109], v205 offset:50176
	ds_read_b64_tr_b16 v[110:111], v205 offset:52736
	ds_read_b64_tr_b16 v[176:177], v205 offset:34880
	ds_read_b64_tr_b16 v[178:179], v205 offset:37440
	ds_read_b64_tr_b16 v[180:181], v205 offset:40000
	ds_read_b64_tr_b16 v[182:183], v205 offset:42560
	ds_read_b64_tr_b16 v[184:185], v205 offset:45120
	ds_read_b64_tr_b16 v[186:187], v205 offset:47680
	s_waitcnt lgkmcnt(12)
	v_mfma_f32_32x32x16_bf16 v[32:47], v[96:99], v[80:83], v[32:47]
	ds_read_b64_tr_b16 v[96:97], v205 offset:50240
	ds_read_b64_tr_b16 v[98:99], v205 offset:52800
	s_waitcnt lgkmcnt(12)
	v_mfma_f32_32x32x16_bf16 v[32:47], v[100:103], v[84:87], v[32:47]
	ds_read_b64_tr_b16 v[100:101], v205 offset:34944
	ds_read_b64_tr_b16 v[102:103], v205 offset:37504
	s_waitcnt lgkmcnt(12)
	v_mfma_f32_32x32x16_bf16 v[32:47], v[104:107], v[88:91], v[32:47]
	ds_read_b64_tr_b16 v[104:105], v205 offset:40064
	ds_read_b64_tr_b16 v[106:107], v205 offset:42624
	s_waitcnt lgkmcnt(12)
	v_mfma_f32_32x32x16_bf16 v[32:47], v[108:111], v[92:95], v[32:47]
	ds_read_b64_tr_b16 v[108:109], v205 offset:45184
	ds_read_b64_tr_b16 v[110:111], v205 offset:47744
	s_waitcnt lgkmcnt(12)
	v_mfma_f32_32x32x16_bf16 v[16:31], v[176:179], v[80:83], v[16:31]
	ds_read_b64_tr_b16 v[176:177], v205 offset:50304
	ds_read_b64_tr_b16 v[178:179], v205 offset:52864
	s_waitcnt lgkmcnt(12)
	v_mfma_f32_32x32x16_bf16 v[16:31], v[180:183], v[84:87], v[16:31]
	ds_read_b64_tr_b16 v[180:181], v205 offset:35008
	ds_read_b64_tr_b16 v[182:183], v205 offset:37568
	s_waitcnt lgkmcnt(12)
	v_mfma_f32_32x32x16_bf16 v[16:31], v[184:187], v[88:91], v[16:31]
	ds_read_b64_tr_b16 v[184:185], v205 offset:40128
	ds_read_b64_tr_b16 v[186:187], v205 offset:42688
	s_waitcnt lgkmcnt(12)
	v_mfma_f32_32x32x16_bf16 v[16:31], v[96:99], v[92:95], v[16:31]
	ds_read_b64_tr_b16 v[96:97], v205 offset:45248
	ds_read_b64_tr_b16 v[98:99], v205 offset:47808
	s_waitcnt lgkmcnt(12)
	v_mfma_f32_32x32x16_bf16 v[0:15], v[100:103], v[80:83], v[0:15]
	ds_read_b64_tr_b16 v[100:101], v205 offset:50368
	ds_read_b64_tr_b16 v[102:103], v205 offset:52928
	s_waitcnt lgkmcnt(12)
	v_mfma_f32_32x32x16_bf16 v[0:15], v[104:107], v[84:87], v[0:15]
	ds_read_b128 v[210:213], v206 offset:8704
	ds_read_b128 v[104:107], v206 offset:8736
	s_waitcnt lgkmcnt(12)
	v_mfma_f32_32x32x16_bf16 v[0:15], v[108:111], v[88:91], v[0:15]
	ds_read_b128 v[108:111], v206 offset:8768
	ds_read_b128 v[188:191], v206
	s_waitcnt lgkmcnt(12)
	v_mfma_f32_32x32x16_bf16 v[0:15], v[176:179], v[92:95], v[0:15]
	ds_read_b128 v[176:179], v206 offset:8800
	ds_read_b128 v[224:227], v206 offset:32
	s_waitcnt lgkmcnt(12)
	v_mfma_f32_32x32x16_bf16 v[48:63], v[180:183], v[80:83], v[48:63]
	ds_read_b128 v[228:231], v206 offset:64
	ds_read_b128 v[248:251], v206 offset:96
	s_waitcnt lgkmcnt(12)
	v_mfma_f32_32x32x16_bf16 v[48:63], v[184:187], v[84:87], v[48:63]
	s_waitcnt lgkmcnt(10)
	v_mfma_f32_32x32x16_bf16 v[48:63], v[96:99], v[88:91], v[48:63]
	s_waitcnt lgkmcnt(8)
	v_mfma_f32_32x32x16_bf16 v[48:63], v[100:103], v[92:95], v[48:63]
	s_waitcnt lgkmcnt(7)
	v_mfma_f32_32x32x16_bf16 v[80:95], v[210:213], v[112:115], v[64:79]
	s_waitcnt lgkmcnt(6)
	v_mfma_f32_32x32x16_bf16 v[80:95], v[104:107], v[116:119], v[80:95]
	s_waitcnt lgkmcnt(5)
	v_mfma_f32_32x32x16_bf16 v[80:95], v[108:111], v[120:123], v[80:95]
	s_waitcnt lgkmcnt(3)
	v_mfma_f32_32x32x16_bf16 v[80:95], v[176:179], v[124:127], v[80:95]
	s_waitcnt lgkmcnt(4)
	v_mfma_f32_32x32x16_bf16 v[96:111], v[188:191], v[112:115], v[64:79]
	s_waitcnt lgkmcnt(2)
	v_mfma_f32_32x32x16_bf16 v[96:111], v[224:227], v[116:119], v[96:111]
	s_waitcnt lgkmcnt(1)
	v_mfma_f32_32x32x16_bf16 v[96:111], v[228:231], v[120:123], v[96:111]
	s_waitcnt lgkmcnt(0)
	v_mfma_f32_32x32x16_bf16 v[96:111], v[248:251], v[124:127], v[96:111]
	s_setprio 0
	s_cmp_gt_i32 s33, 2
	s_cbranch_scc0 .Lba_a1

.LA2_top:
	s_setprio 1
	v_add_u32_e32 v205, 0x5000, v165
	v_add_u32_e32 v206, 0x20400, v192
	ds_read_b64_tr_b16 v[96:97], v205 offset:34816
	ds_read_b64_tr_b16 v[98:99], v205 offset:37376
	ds_read_b64_tr_b16 v[100:101], v205 offset:39936
	ds_read_b64_tr_b16 v[102:103], v205 offset:42496
	ds_read_b64_tr_b16 v[104:105], v205 offset:45056
	ds_read_b64_tr_b16 v[106:107], v205 offset:47616
	ds_read_b64_tr_b16 v[108:109], v205 offset:50176
	ds_read_b64_tr_b16 v[110:111], v205 offset:52736
	ds_read_b64_tr_b16 v[176:177], v205 offset:34880
	ds_read_b64_tr_b16 v[178:179], v205 offset:37440
	ds_read_b64_tr_b16 v[180:181], v205 offset:40000
	ds_read_b64_tr_b16 v[182:183], v205 offset:42560
	ds_read_b64_tr_b16 v[184:185], v205 offset:45120
	ds_read_b64_tr_b16 v[186:187], v205 offset:47680
	s_waitcnt lgkmcnt(12)
	v_mfma_f32_32x32x16_bf16 v[32:47], v[96:99], v[80:83], v[32:47]
	ds_read_b64_tr_b16 v[96:97], v205 offset:50240
	ds_read_b64_tr_b16 v[98:99], v205 offset:52800
	s_waitcnt lgkmcnt(12)
	v_mfma_f32_32x32x16_bf16 v[32:47], v[100:103], v[84:87], v[32:47]
	ds_read_b64_tr_b16 v[100:101], v205 offset:34944
	ds_read_b64_tr_b16 v[102:103], v205 offset:37504
	s_waitcnt lgkmcnt(12)
	v_mfma_f32_32x32x16_bf16 v[32:47], v[104:107], v[88:91], v[32:47]
	ds_read_b64_tr_b16 v[104:105], v205 offset:40064
	ds_read_b64_tr_b16 v[106:107], v205 offset:42624
	s_waitcnt lgkmcnt(12)
	v_mfma_f32_32x32x16_bf16 v[32:47], v[108:111], v[92:95], v[32:47]
	ds_read_b64_tr_b16 v[108:109], v205 offset:45184
	ds_read_b64_tr_b16 v[110:111], v205 offset:47744
	s_waitcnt lgkmcnt(12)
	v_mfma_f32_32x32x16_bf16 v[16:31], v[176:179], v[80:83], v[16:31]
	ds_read_b64_tr_b16 v[176:177], v205 offset:50304
	ds_read_b64_tr_b16 v[178:179], v205 offset:52864
	s_waitcnt lgkmcnt(12)
	v_mfma_f32_32x32x16_bf16 v[16:31], v[180:183], v[84:87], v[16:31]
	ds_read_b64_tr_b16 v[180:181], v205 offset:35008
	ds_read_b64_tr_b16 v[182:183], v205 offset:37568
	s_waitcnt lgkmcnt(12)
	v_mfma_f32_32x32x16_bf16 v[16:31], v[184:187], v[88:91], v[16:31]
	ds_read_b64_tr_b16 v[184:185], v205 offset:40128
	ds_read_b64_tr_b16 v[186:187], v205 offset:42688
	s_waitcnt lgkmcnt(12)
	v_mfma_f32_32x32x16_bf16 v[16:31], v[96:99], v[92:95], v[16:31]
	ds_read_b64_tr_b16 v[96:97], v205 offset:45248
	ds_read_b64_tr_b16 v[98:99], v205 offset:47808
	s_waitcnt lgkmcnt(12)
	v_mfma_f32_32x32x16_bf16 v[0:15], v[100:103], v[80:83], v[0:15]
	ds_read_b64_tr_b16 v[100:101], v205 offset:50368
	ds_read_b64_tr_b16 v[102:103], v205 offset:52928
	s_waitcnt lgkmcnt(12)
	v_mfma_f32_32x32x16_bf16 v[0:15], v[104:107], v[84:87], v[0:15]
	ds_read_b128 v[210:213], v206 offset:8704
	ds_read_b128 v[104:107], v206 offset:8736
	s_waitcnt lgkmcnt(12)
	v_mfma_f32_32x32x16_bf16 v[0:15], v[108:111], v[88:91], v[0:15]
	ds_read_b128 v[108:111], v206 offset:8768
	ds_read_b128 v[188:191], v206
	s_waitcnt lgkmcnt(12)
	v_mfma_f32_32x32x16_bf16 v[0:15], v[176:179], v[92:95], v[0:15]
	ds_read_b128 v[176:179], v206 offset:8800
	ds_read_b128 v[224:227], v206 offset:32
	s_waitcnt lgkmcnt(12)
	v_mfma_f32_32x32x16_bf16 v[48:63], v[180:183], v[80:83], v[48:63]
	ds_read_b128 v[228:231], v206 offset:64
	ds_read_b128 v[248:251], v206 offset:96
	s_waitcnt lgkmcnt(12)
	v_mfma_f32_32x32x16_bf16 v[48:63], v[184:187], v[84:87], v[48:63]
	s_waitcnt lgkmcnt(10)
	v_mfma_f32_32x32x16_bf16 v[48:63], v[96:99], v[88:91], v[48:63]
	s_waitcnt lgkmcnt(8)
	v_mfma_f32_32x32x16_bf16 v[48:63], v[100:103], v[92:95], v[48:63]
	s_waitcnt lgkmcnt(7)
	v_mfma_f32_32x32x16_bf16 v[80:95], v[210:213], v[112:115], v[64:79]
	s_waitcnt lgkmcnt(6)
	v_mfma_f32_32x32x16_bf16 v[80:95], v[104:107], v[116:119], v[80:95]
	s_waitcnt lgkmcnt(5)
	v_mfma_f32_32x32x16_bf16 v[80:95], v[108:111], v[120:123], v[80:95]
	s_waitcnt lgkmcnt(3)
	v_mfma_f32_32x32x16_bf16 v[80:95], v[176:179], v[124:127], v[80:95]
	s_waitcnt lgkmcnt(4)
	v_mfma_f32_32x32x16_bf16 v[96:111], v[188:191], v[112:115], v[64:79]
	s_waitcnt lgkmcnt(2)
	v_mfma_f32_32x32x16_bf16 v[96:111], v[224:227], v[116:119], v[96:111]
	s_waitcnt lgkmcnt(1)
	v_mfma_f32_32x32x16_bf16 v[96:111], v[228:231], v[120:123], v[96:111]
	s_waitcnt lgkmcnt(0)
	v_mfma_f32_32x32x16_bf16 v[96:111], v[248:251], v[124:127], v[96:111]
	s_setprio 0
	s_cmp_gt_i32 s33, 2
	s_cbranch_scc0 .Lba_a2

.LA0_top:
	s_setprio 1
	v_add_u32_e32 v205, 0xa000, v165
	v_add_u32_e32 v206, 0x0, v192
	ds_read_b64_tr_b16 v[96:97], v205 offset:34816
	ds_read_b64_tr_b16 v[98:99], v205 offset:37376
	ds_read_b64_tr_b16 v[100:101], v205 offset:39936
	ds_read_b64_tr_b16 v[102:103], v205 offset:42496
	ds_read_b64_tr_b16 v[104:105], v205 offset:45056
	ds_read_b64_tr_b16 v[106:107], v205 offset:47616
	ds_read_b64_tr_b16 v[108:109], v205 offset:50176
	ds_read_b64_tr_b16 v[110:111], v205 offset:52736
	ds_read_b64_tr_b16 v[176:177], v205 offset:34880
	ds_read_b64_tr_b16 v[178:179], v205 offset:37440
	ds_read_b64_tr_b16 v[180:181], v205 offset:40000
	ds_read_b64_tr_b16 v[182:183], v205 offset:42560
	ds_read_b64_tr_b16 v[184:185], v205 offset:45120
	ds_read_b64_tr_b16 v[186:187], v205 offset:47680
	s_waitcnt lgkmcnt(12)
	v_mfma_f32_32x32x16_bf16 v[32:47], v[96:99], v[80:83], v[32:47]
	ds_read_b64_tr_b16 v[96:97], v205 offset:50240
	ds_read_b64_tr_b16 v[98:99], v205 offset:52800
	s_waitcnt lgkmcnt(12)
	v_mfma_f32_32x32x16_bf16 v[32:47], v[100:103], v[84:87], v[32:47]
	ds_read_b64_tr_b16 v[100:101], v205 offset:34944
	ds_read_b64_tr_b16 v[102:103], v205 offset:37504
	s_waitcnt lgkmcnt(12)
	v_mfma_f32_32x32x16_bf16 v[32:47], v[104:107], v[88:91], v[32:47]
	ds_read_b64_tr_b16 v[104:105], v205 offset:40064
	ds_read_b64_tr_b16 v[106:107], v205 offset:42624
	s_waitcnt lgkmcnt(12)
	v_mfma_f32_32x32x16_bf16 v[32:47], v[108:111], v[92:95], v[32:47]
	ds_read_b64_tr_b16 v[108:109], v205 offset:45184
	ds_read_b64_tr_b16 v[110:111], v205 offset:47744
	s_waitcnt lgkmcnt(12)
	v_mfma_f32_32x32x16_bf16 v[16:31], v[176:179], v[80:83], v[16:31]
	ds_read_b64_tr_b16 v[176:177], v205 offset:50304
	ds_read_b64_tr_b16 v[178:179], v205 offset:52864
	s_waitcnt lgkmcnt(12)
	v_mfma_f32_32x32x16_bf16 v[16:31], v[180:183], v[84:87], v[16:31]
	ds_read_b64_tr_b16 v[180:181], v205 offset:35008
	ds_read_b64_tr_b16 v[182:183], v205 offset:37568
	s_waitcnt lgkmcnt(12)
	v_mfma_f32_32x32x16_bf16 v[16:31], v[184:187], v[88:91], v[16:31]
	ds_read_b64_tr_b16 v[184:185], v205 offset:40128
	ds_read_b64_tr_b16 v[186:187], v205 offset:42688
	s_waitcnt lgkmcnt(12)
	v_mfma_f32_32x32x16_bf16 v[16:31], v[96:99], v[92:95], v[16:31]
	ds_read_b64_tr_b16 v[96:97], v205 offset:45248
	ds_read_b64_tr_b16 v[98:99], v205 offset:47808
	s_waitcnt lgkmcnt(12)
	v_mfma_f32_32x32x16_bf16 v[0:15], v[100:103], v[80:83], v[0:15]
	ds_read_b64_tr_b16 v[100:101], v205 offset:50368
	ds_read_b64_tr_b16 v[102:103], v205 offset:52928
	s_waitcnt lgkmcnt(12)
	v_mfma_f32_32x32x16_bf16 v[0:15], v[104:107], v[84:87], v[0:15]
	ds_read_b128 v[210:213], v206 offset:8704
	ds_read_b128 v[104:107], v206 offset:8736
	s_waitcnt lgkmcnt(12)
	v_mfma_f32_32x32x16_bf16 v[0:15], v[108:111], v[88:91], v[0:15]
	ds_read_b128 v[108:111], v206 offset:8768
	ds_read_b128 v[188:191], v206
	s_waitcnt lgkmcnt(12)
	v_mfma_f32_32x32x16_bf16 v[0:15], v[176:179], v[92:95], v[0:15]
	ds_read_b128 v[176:179], v206 offset:8800
	ds_read_b128 v[224:227], v206 offset:32
	s_waitcnt lgkmcnt(12)
	v_mfma_f32_32x32x16_bf16 v[48:63], v[180:183], v[80:83], v[48:63]
	ds_read_b128 v[228:231], v206 offset:64
	ds_read_b128 v[248:251], v206 offset:96
	s_waitcnt lgkmcnt(12)
	v_mfma_f32_32x32x16_bf16 v[48:63], v[184:187], v[84:87], v[48:63]
	s_waitcnt lgkmcnt(10)
	v_mfma_f32_32x32x16_bf16 v[48:63], v[96:99], v[88:91], v[48:63]
	s_waitcnt lgkmcnt(8)
	v_mfma_f32_32x32x16_bf16 v[48:63], v[100:103], v[92:95], v[48:63]
	s_waitcnt lgkmcnt(7)
	v_mfma_f32_32x32x16_bf16 v[80:95], v[210:213], v[112:115], v[64:79]
	s_waitcnt lgkmcnt(6)
	v_mfma_f32_32x32x16_bf16 v[80:95], v[104:107], v[116:119], v[80:95]
	s_waitcnt lgkmcnt(5)
	v_mfma_f32_32x32x16_bf16 v[80:95], v[108:111], v[120:123], v[80:95]
	s_waitcnt lgkmcnt(3)
	v_mfma_f32_32x32x16_bf16 v[80:95], v[176:179], v[124:127], v[80:95]
	s_waitcnt lgkmcnt(4)
	v_mfma_f32_32x32x16_bf16 v[96:111], v[188:191], v[112:115], v[64:79]
	s_waitcnt lgkmcnt(2)
	v_mfma_f32_32x32x16_bf16 v[96:111], v[224:227], v[116:119], v[96:111]
	s_waitcnt lgkmcnt(1)
	v_mfma_f32_32x32x16_bf16 v[96:111], v[228:231], v[120:123], v[96:111]
	s_waitcnt lgkmcnt(0)
	v_mfma_f32_32x32x16_bf16 v[96:111], v[248:251], v[124:127], v[96:111]
	s_setprio 0
	s_cmp_gt_i32 s33, 2
	s_cbranch_scc0 .Lba_a0
